# attention loop: four wave groups staggered by quarter tiles (conditional barrier sites), interleaved schedule, 6-deep V ring; same math
# baseline (speedup 1.0000x reference)
; #define SLOAD(i, k0) do { sr_[i].a0 = *reinterpret_cast<const bf16x8*>(&KVh[(size_t)((k0) + sr) * NKV + c16 * 8]); sr_[i].a1 = *reinterpret_cast<const bf16x8*>(&KVh[(size_t)((k0) + 32 + sr) * NKV + c16 * 8]); \
;     sr_[i].rr = *reinterpret_cast<const bf16x8*>(&KR[(size_t)((k0) + rkey) * 32 + rch * 8]); } while (0)
; #define SWRITE(b, i) do { if (isK) { *(bf16x8*)(K_lds + (b) * SHM_K + kst0) = sr_[i].a0; *(bf16x8*)(K_lds + (b) * SHM_K + kst1) = sr_[i].a1; } \
;     else { *(bf16x8*)(V_lds + (b) * SHM_V + vst0) = sr_[i].a0; *(bf16x8*)(V_lds + (b) * SHM_V + vst1) = sr_[i].a1; } \
;     if (rwr) *(bf16x8*)(K_lds + (b) * SHM_K + rst) = sr_[i].rr; } while (0)
; #define SWAIT() asm volatile("s_waitcnt vmcnt(3)" ::: "memory")
; __device__ __forceinline__ void attn_body(const bf16_t* __restrict__ Qb, const bf16_t* __restrict__ KVh, const bf16_t* __restrict__ KR, const float* __restrict__ ropeq,
;                                           bf16_t* __restrict__ Ob, int seq, char* lds, const int tid) {
;     ...
;     f32x16 pA0, pA1, pB0, pB1; float mnA, mnB, alA, alB; bf16x8 pa0, pa1, pa2, pa3; const int NT = seq / KVBLK;
;     constexpr int SE = 0, SO = 1;
;     SLOAD(SE, 0); asm volatile("s_waitcnt vmcnt(0)" ::: "memory"); SWRITE(0, SE); __syncthreads();
;     qkt(pA0, pA1, K_lds, qr, r32, hi); partialSM(pA0, pA1, m_reg, mnA, alA);
;     SLOAD(SO, KVBLK); if (2 < NT) SLOAD(SE, 2 * KVBLK);
;     SWAIT(); SWRITE(1, SO); __syncthreads();
;     int bp = 0, bc = 1, bn = 2;
.LBB0_51:
	s_or_b64 exec, exec, s[14:15]
	s_waitcnt vmcnt(3)
	v_max_f32_e32 v33, 0xf149f2ca, v44
	v_mov_b32_e32 v32, 0xf149f2ca
	v_cndmask_b32_e32 v179, v33, v32, vcc
	v_mul_f32_e32 v32, 0xbe16c740, v179
	v_pk_fma_f32 v[16:17], v[16:17], s[52:53], v[32:33] op_sel_hi:[1,0,0]
	s_lshr_b32 s14, s20, 4
	v_exp_f32_e32 v116, v16
	v_sub_f32_e32 v16, 0xf149f2ca, v33
	v_mul_f32_e32 v16, 0x3e16c740, v16
	v_exp_f32_e32 v16, v16
	v_pk_fma_f32 v[18:19], v[18:19], s[52:53], v[32:33] op_sel_hi:[1,0,0]
	v_pk_fma_f32 v[20:21], v[20:21], s[52:53], v[32:33] op_sel_hi:[1,0,0]
	v_pk_fma_f32 v[22:23], v[22:23], s[52:53], v[32:33] op_sel_hi:[1,0,0]
	v_pk_fma_f32 v[24:25], v[24:25], s[52:53], v[32:33] op_sel_hi:[1,0,0]
	v_pk_fma_f32 v[26:27], v[26:27], s[52:53], v[32:33] op_sel_hi:[1,0,0]
	v_pk_fma_f32 v[28:29], v[28:29], s[52:53], v[32:33] op_sel_hi:[1,0,0]
	v_pk_fma_f32 v[30:31], v[30:31], s[52:53], v[32:33] op_sel_hi:[1,0,0]
	s_and_b32 s14, s14, 15
	v_exp_f32_e32 v117, v17
	v_exp_f32_e32 v114, v18
	v_exp_f32_e32 v115, v19
	v_exp_f32_e32 v112, v20
	v_exp_f32_e32 v113, v21
	v_exp_f32_e32 v110, v22
	v_exp_f32_e32 v111, v23
	v_exp_f32_e32 v108, v24
	v_exp_f32_e32 v109, v25
	v_exp_f32_e32 v106, v26
	v_exp_f32_e32 v107, v27
	v_exp_f32_e32 v102, v28
	v_exp_f32_e32 v103, v29
	v_exp_f32_e32 v104, v30
	v_exp_f32_e32 v105, v31
	s_lshl_b32 s14, s14, 8
	v_pk_fma_f32 v[118:119], v[14:15], s[52:53], v[32:33] op_sel_hi:[1,0,0]
	s_add_u32 s6, s14, s6
	v_mov_b32_e32 v14, v65
	v_mov_b32_e32 v15, v65
	v_cndmask_b32_e64 v225, v16, 1.0, vcc
	v_pk_fma_f32 v[120:121], v[12:13], s[52:53], v[32:33] op_sel_hi:[1,0,0]
	v_pk_fma_f32 v[122:123], v[10:11], s[52:53], v[32:33] op_sel_hi:[1,0,0]
	v_pk_fma_f32 v[124:125], v[8:9], s[52:53], v[32:33] op_sel_hi:[1,0,0]
	v_pk_fma_f32 v[126:127], v[6:7], s[52:53], v[32:33] op_sel_hi:[1,0,0]
	v_pk_fma_f32 v[128:129], v[4:5], s[52:53], v[32:33] op_sel_hi:[1,0,0]
	v_pk_fma_f32 v[176:177], v[2:3], s[52:53], v[32:33] op_sel_hi:[1,0,0]
	v_pk_fma_f32 v[180:181], v[0:1], s[52:53], v[32:33] op_sel_hi:[1,0,0]
	s_addc_u32 s7, 0, s7
	v_mov_b32_e32 v0, v65
	v_mov_b32_e32 v1, v65
	v_mov_b32_e32 v2, v65
	v_mov_b32_e32 v3, v65
	v_mov_b32_e32 v4, v65
	v_mov_b32_e32 v5, v65
	v_mov_b32_e32 v6, v65
	v_mov_b32_e32 v7, v65
	v_mov_b32_e32 v8, v65
	v_mov_b32_e32 v9, v65
	v_mov_b32_e32 v10, v65
	v_mov_b32_e32 v11, v65
	v_mov_b32_e32 v12, v65
	v_mov_b32_e32 v13, v65
	v_mov_b64_e32 v[30:31], v[14:15]
	v_lshl_add_u64 v[168:169], s[6:7], 0, v[156:157]
	v_lshl_add_u64 v[170:171], v[158:159], 0, s[12:13]
	v_lshl_add_u64 v[172:173], v[160:161], 0, s[12:13]
	s_mov_b32 s16, 0
	v_mov_b32_e32 v163, 0
	s_mov_b32 s6, 2
	s_mov_b32 s17, 1
	v_mov_b64_e32 v[28:29], v[12:13]
	v_mov_b64_e32 v[26:27], v[10:11]
	v_mov_b64_e32 v[24:25], v[8:9]
	v_mov_b64_e32 v[22:23], v[6:7]
	v_mov_b64_e32 v[20:21], v[4:5]
	v_mov_b64_e32 v[18:19], v[2:3]
	v_mov_b64_e32 v[16:17], v[0:1]
	s_mov_b32 s18, 1
	s_load_dwordx2 s[26:27], s[94:95], 0xb8
	s_mov_b32 s24, 0x2000
	s_mov_b32 s25, 0
	s_mov_b32 s58, 0
	s_mov_b32 s59, 0
	s_mov_b32 s60, 0x400
	v_readfirstlane_b32 s47, v140
	s_lshr_b32 s47, s47, 7
	s_waitcnt lgkmcnt(0)
	s_add_u32 s28, s26, 0x10cc0000
	s_addc_u32 s29, s27, 0
	s_add_u32 s30, s26, 0x10ce0000
	s_addc_u32 s31, s27, 0
	s_add_u32 s40, s26, 0x10d00000
	s_addc_u32 s41, s27, 0
	s_add_u32 s42, s26, 0x10d20000
	s_addc_u32 s43, s27, 0
	s_waitcnt lgkmcnt(0)
	s_barrier

; #define SBAR() __builtin_amdgcn_sched_barrier(0)
; __device__ __forceinline__ void qkt(f32x16& p0, f32x16& p1, const char* Ks, const bf16x8* qr, int r32, int hi) {
;     p0 = f32x16{}; p1 = f32x16{};
; #pragma unroll
;     for (int d0 = 0; d0 < 6; ++d0) { const int cb = (d0 * 16 + hi * 8) * 2;
;         bf16x8 b0 = *reinterpret_cast<const bf16x8*>(Ks + KSWZ(r32, cb));
;         bf16x8 b1 = *reinterpret_cast<const bf16x8*>(Ks + KSWZ(32 + r32, cb));
;         p0 = __builtin_amdgcn_mfma_f32_32x32x16_bf16(b0, qr[d0], p0, 0, 0, 0);
;         p1 = __builtin_amdgcn_mfma_f32_32x32x16_bf16(b1, qr[d0], p1, 0, 0, 0); }
; }
; __device__ __forceinline__ int v_st(int k, int c) { const int kk = (k & ~0xC) | ((k & 4) << 1) | ((k & 8) >> 1); return ((kk >> 3) * 4 + (c >> 5)) * 512 + ((kk & 7) * 32 + (c & 31)) * 2; }
; __device__ __forceinline__ int v_rd_base(int lane) { return ((lane & 3) << 3) | (((lane >> 2) & 3) << 6) | (((lane >> 4) & 1) << 5) | (((lane >> 5) & 1) << 8); }
; template <int OFF> __device__ __forceinline__ s16x4 tr_read(int vb) {
;     s16x4 r; asm volatile("ds_read_b64_tr_b16 %0, %1 offset:%2" : "=&v"(r) : "v"(vb), "i"(OFF) : "memory"); return r;
; }
; template <int D0> __device__ __forceinline__ void pv_one(f32x16& od, int vb, bf16x8 pa0, bf16x8 pa1, bf16x8 pa2, bf16x8 pa3) {
;     const s16x4 l0 = tr_read<v_rd_off(D0, 0, 0)>(vb), h0 = tr_read<v_rd_off(D0, 0, 1)>(vb), l1 = tr_read<v_rd_off(D0, 1, 0)>(vb), h1 = tr_read<v_rd_off(D0, 1, 1)>(vb);
;     const s16x4 l2 = tr_read<v_rd_off(D0, 2, 0)>(vb), h2 = tr_read<v_rd_off(D0, 2, 1)>(vb), l3 = tr_read<v_rd_off(D0, 3, 0)>(vb), h3 = tr_read<v_rd_off(D0, 3, 1)>(vb);
;     asm volatile("s_waitcnt lgkmcnt(0)" ::: "memory"); SBAR();
;     ...
;     od = __builtin_amdgcn_mfma_f32_32x32x16_bf16(pa0, PK(l0, h0), od, 0, 0, 0);
;     od = __builtin_amdgcn_mfma_f32_32x32x16_bf16(pa1, PK(l1, h1), od, 0, 0, 0);
;     od = __builtin_amdgcn_mfma_f32_32x32x16_bf16(pa2, PK(l2, h2), od, 0, 0, 0);
;     od = __builtin_amdgcn_mfma_f32_32x32x16_bf16(pa3, PK(l3, h3), od, 0, 0, 0);
;     ...
; }
; __device__ __forceinline__ void attn_body(const bf16_t* __restrict__ Qb, const bf16_t* __restrict__ KVh, const bf16_t* __restrict__ KR, const float* __restrict__ ropeq,
;                                           bf16_t* __restrict__ Ob, int seq, char* lds, const int tid) {
;     ...
;         SBAR(); qkt(pB0, pB1, K_lds + bc * SHM_K, qr, r32, hi);
.Lattn_swB:
	s_waitcnt lgkmcnt(4)
	v_mfma_f32_32x32x16_bf16 v[32:47], v[238:241], v[70:73], v[32:47]
	v_add_u32_e32 v254, s14, v214
	ds_read_b128 v[234:237], v254 offset:49152
	ds_read_b128 v[238:241], v254 offset:57344
	v_exp_f32_e32 v128, v128
	v_exp_f32_e32 v129, v129
	v_exp_f32_e32 v202, v126
	v_exp_f32_e32 v203, v127
	s_waitcnt lgkmcnt(5)
	v_mfma_f32_32x32x16_bf16 v[48:63], v[242:245], v[66:69], v[48:63]
	v_add_f32_e32 v174, v180, v176
	v_add_f32_e32 v175, v181, v177
	v_add_f32_e32 v174, v128, v174
	v_add_f32_e32 v175, v129, v175
	v_add_f32_e32 v174, v202, v174
	v_add_f32_e32 v175, v203, v175
	v_add_f32_e32 v174, v226, v174
	v_add_f32_e32 v175, v227, v175
	v_lshl_add_u64 v[106:107], s[28:29], 0, v[168:169]
	global_load_dwordx4 v[106:109], v[106:107], off
	v_lshl_add_u64 v[110:111], s[30:31], 0, v[168:169]
	global_load_dwordx4 v[110:113], v[110:111], off
	v_lshl_add_u64 v[102:103], s[26:27], 0, v[172:173]
	global_load_dwordx4 v[102:105], v[102:103], off
	s_waitcnt lgkmcnt(4)
	v_mfma_f32_32x32x16_bf16 v[32:47], v[246:249], v[66:69], v[32:47]
	v_add_u32_e32 v254, s14, v215
	ds_read_b128 v[242:245], v254 offset:49152
	ds_read_b128 v[246:249], v254 offset:57344
	v_add_f32_e32 v174, v228, v174
	v_add_f32_e32 v175, v229, v175
	v_add_f32_e32 v174, v230, v174
	v_add_f32_e32 v175, v231, v175
	v_add_f32_e32 v174, v232, v174
	v_add_f32_e32 v175, v233, v175
	v_add_f32_e32 v250, v250, v174
	v_add_f32_e32 v251, v251, v175
	s_waitcnt lgkmcnt(3)
	v_mfma_f32_32x32x16_bf16 v[48:63], v[234:237], v[82:85], v[48:63]
	v_add_f32_e32 v174, v250, v251
	v_add_f32_e32 v175, v251, v250
	v_mov_b32_e32 v175, v174
	s_nop 1
	v_permlane32_swap_b32_e32 v174, v175
	v_cvt_pk_bf16_f32 v124, v180, v181
	s_waitcnt lgkmcnt(2)
	v_mfma_f32_32x32x16_bf16 v[32:47], v[238:241], v[82:85], v[32:47]
	v_add_u32_e32 v255, s61, v185
	ds_read_b64_tr_b16 v[234:235], v255 offset:0
	ds_read_b64_tr_b16 v[236:237], v255 offset:2048
	ds_read_b64_tr_b16 v[238:239], v255 offset:4096
	ds_read_b64_tr_b16 v[240:241], v255 offset:6144
	v_cvt_pk_bf16_f32 v125, v176, v177
	v_cvt_pk_bf16_f32 v126, v128, v129
	v_cvt_pk_bf16_f32 v127, v202, v203
	s_nop 0
	v_permlane32_swap_b32_e32 v124, v126
	s_cmp_eq_u32 s47, 3
	s_cbranch_scc0 .Lattn_gb1
	s_waitcnt lgkmcnt(0)
	s_barrier
.Lattn_gb1:
	s_waitcnt lgkmcnt(5)
	v_mfma_f32_32x32x16_bf16 v[48:63], v[242:245], v[86:89], v[48:63]
	v_permlane32_swap_b32_e32 v125, v127
	v_cvt_pk_bf16_f32 v226, v226, v227
	v_cvt_pk_bf16_f32 v227, v228, v229
	v_cvt_pk_bf16_f32 v228, v230, v231
	s_waitcnt lgkmcnt(4)
	v_mfma_f32_32x32x16_bf16 v[32:47], v[246:249], v[86:89], v[32:47]
	ds_read_b64_tr_b16 v[242:243], v255 offset:8192
	ds_read_b64_tr_b16 v[244:245], v255 offset:10240
	ds_read_b64_tr_b16 v[246:247], v255 offset:12288
	ds_read_b64_tr_b16 v[248:249], v255 offset:14336
	v_cvt_pk_bf16_f32 v229, v232, v233
	v_permlane32_swap_b32_e32 v226, v228
	s_nop 0
	v_permlane32_swap_b32_e32 v227, v229
	s_cmp_eq_u32 s47, 2
	s_cbranch_scc0 .Lattn_gb2
	s_waitcnt lgkmcnt(0)
	s_barrier
.Lattn_gb2:
	s_waitcnt lgkmcnt(6)
	v_mfma_f32_32x32x16_bf16 v[0:15], v[116:119], v[234:237], v[0:15]
	ds_read_b64_tr_b16 v[234:235], v255 offset:512
	ds_read_b64_tr_b16 v[236:237], v255 offset:2560
	v_max_f32_e32 v90, v48, v49
	v_max_f32_e32 v91, v32, v33
	v_max3_f32 v90, v90, v50, v51
	v_max3_f32 v91, v91, v34, v35
	v_max3_f32 v90, v90, v52, v53
	v_max3_f32 v91, v91, v36, v37
	s_waitcnt lgkmcnt(6)
	v_mfma_f32_32x32x16_bf16 v[0:15], v[120:123], v[238:241], v[0:15]
	ds_read_b64_tr_b16 v[238:239], v255 offset:4608
	ds_read_b64_tr_b16 v[240:241], v255 offset:6656
	v_max3_f32 v90, v90, v54, v55
	v_max3_f32 v91, v91, v38, v39
	v_max3_f32 v90, v90, v56, v57
	v_max3_f32 v91, v91, v40, v41
	v_max3_f32 v90, v90, v58, v59
	v_max3_f32 v91, v91, v42, v43
	v_max3_f32 v90, v90, v60, v61
	s_waitcnt lgkmcnt(6)
	v_mfma_f32_32x32x16_bf16 v[0:15], v[124:127], v[242:245], v[0:15]
	ds_read_b64_tr_b16 v[242:243], v255 offset:8704
	ds_read_b64_tr_b16 v[244:245], v255 offset:10752
	v_max3_f32 v91, v91, v44, v45
	v_max3_f32 v90, v90, v62, v63
	v_max3_f32 v91, v91, v46, v47
	v_max_f32_e32 v90, v90, v91
	v_mov_b32_e32 v91, v90
	s_nop 1
	v_permlane32_swap_b32_e32 v90, v91
	v_max_f32_e32 v90, v90, v91
	s_waitcnt lgkmcnt(6)
	v_mfma_f32_32x32x16_bf16 v[0:15], v[226:229], v[246:249], v[0:15]
	ds_read_b64_tr_b16 v[246:247], v255 offset:12800
	ds_read_b64_tr_b16 v[248:249], v255 offset:14848
	v_sub_f32_e32 v92, v90, v179
	v_cmp_ge_f32_e32 vcc, s67, v92
	v_max_f32_e32 v90, v179, v90
	v_sub_f32_e32 v92, v179, v90
	v_mul_f32_e32 v92, 0x3e16c740, v92
	v_exp_f32_e32 v93, v92
	s_cmp_eq_u32 s47, 1
	s_cbranch_scc0 .Lattn_gb3
	s_waitcnt lgkmcnt(0)
	s_barrier
; #define SWRITE(b, i) do { if (isK) { *(bf16x8*)(K_lds + (b) * SHM_K + kst0) = sr_[i].a0; *(bf16x8*)(K_lds + (b) * SHM_K + kst1) = sr_[i].a1; } \
;     else { *(bf16x8*)(V_lds + (b) * SHM_V + vst0) = sr_[i].a0; *(bf16x8*)(V_lds + (b) * SHM_V + vst1) = sr_[i].a1; } \
;     if (rwr) *(bf16x8*)(K_lds + (b) * SHM_K + rst) = sr_[i].rr; } while (0)
; #define SWAIT() asm volatile("s_waitcnt vmcnt(3)" ::: "memory")
; __device__ __forceinline__ void partialSM(f32x16& p0, f32x16& p1, float& m_reg, float& mn, float& alpha) {
;     constexpr float Cc = SCALE * 1.4426950408889634f;
;     float pmax = p0[0];
; #pragma unroll
;     for (int r = 1; r < 16; ++r) pmax = fmaxf(pmax, p0[r]);
; #pragma unroll
;     for (int r = 0; r < 16; ++r) pmax = fmaxf(pmax, p1[r]);
;     { auto rr = __builtin_amdgcn_permlane32_swap(__float_as_uint(pmax), __float_as_uint(pmax), false, false);
;       pmax = fmaxf(__uint_as_float(rr[0]), __uint_as_float(rr[1])); }
;     if (__builtin_expect(__all(pmax - m_reg <= THR / SCALE), 1)) { mn = m_reg; alpha = 1.f; }
;     else { mn = fmaxf(m_reg, pmax); alpha = __builtin_amdgcn_exp2f((m_reg - mn) * Cc); m_reg = mn; }
;     const float mnC = -mn * Cc;
;     { typedef float f32x2 __attribute__((ext_vector_type(2))); const f32x2 c2 = {Cc, Cc}, m2 = {mnC, mnC};
; #pragma unroll
;       for (int r = 0; r < 16; r += 2) { f32x2 t = {p0[r], p0[r + 1]}; t = __builtin_elementwise_fma(t, c2, m2); p0[r] = t.x; p0[r + 1] = t.y; }
; #pragma unroll
;       for (int r = 0; r < 16; r += 2) { f32x2 t = {p1[r], p1[r + 1]}; t = __builtin_elementwise_fma(t, c2, m2); p1[r] = t.x; p1[r + 1] = t.y; } }
; #pragma unroll
;     for (int r = 0; r < 16; ++r) p0[r] = __builtin_amdgcn_exp2f(p0[r]);
; }
; __device__ __forceinline__ void attn_body(const bf16_t* __restrict__ Qb, const bf16_t* __restrict__ KVh, const bf16_t* __restrict__ KR, const float* __restrict__ ropeq,
;                                           bf16_t* __restrict__ Ob, int seq, char* lds, const int tid) {
;     ...
;         pv_d0(o, vb0 + bp * (int)SHM_V, pa0, pa1, pa2, pa3); partialSM(pB0, pB1, m_reg, mnB, alB);
;         SWAIT(); SWRITE(bn, SE);
;         RESC(alB); __syncthreads();
.Lattn_gb3:
	s_waitcnt lgkmcnt(6)
	v_mfma_f32_32x32x16_bf16 v[16:31], v[116:119], v[234:237], v[16:31]
	s_cmp_eq_u64 vcc, exec
	s_cselect_b64 s[44:45], -1, 0
	v_cndmask_b32_e64 v180, v90, v179, s[44:45]
	v_mul_f32_e32 v94, 0xbe16c740, v180
	v_fma_f32 v48, v48, s52, v94
	v_fma_f32 v49, v49, s52, v94
	v_fma_f32 v50, v50, s52, v94
	v_fma_f32 v51, v51, s52, v94
	v_fma_f32 v52, v52, s52, v94
	v_fma_f32 v53, v53, s52, v94
	v_exp_f32_e32 v234, v50
	v_exp_f32_e32 v235, v51
	v_exp_f32_e32 v236, v52
	v_exp_f32_e32 v237, v53
	s_waitcnt lgkmcnt(4)
	v_mfma_f32_32x32x16_bf16 v[16:31], v[120:123], v[238:241], v[16:31]
	v_fma_f32 v54, v54, s52, v94
	v_fma_f32 v55, v55, s52, v94
	v_fma_f32 v56, v56, s52, v94
	v_fma_f32 v57, v57, s52, v94
	v_fma_f32 v58, v58, s52, v94
	v_fma_f32 v59, v59, s52, v94
	v_fma_f32 v60, v60, s52, v94
	v_fma_f32 v61, v61, s52, v94
	v_fma_f32 v62, v62, s52, v94
	v_fma_f32 v63, v63, s52, v94
	v_fma_f32 v128, v38, s52, v94
	v_fma_f32 v129, v39, s52, v94
	v_exp_f32_e32 v238, v54
	v_exp_f32_e32 v239, v55
	v_exp_f32_e32 v240, v56
	v_exp_f32_e32 v241, v57
	v_fma_f32 v122, v32, s52, v94
	v_fma_f32 v123, v33, s52, v94
	s_waitcnt lgkmcnt(2)
	v_mfma_f32_32x32x16_bf16 v[16:31], v[124:127], v[242:245], v[16:31]
	v_fma_f32 v178, v40, s52, v94
	v_fma_f32 v179, v41, s52, v94
	v_fma_f32 v202, v42, s52, v94
	v_fma_f32 v203, v43, s52, v94
	v_fma_f32 v230, v46, s52, v94
	v_fma_f32 v231, v47, s52, v94
	v_exp_f32_e32 v232, v48
	v_exp_f32_e32 v233, v49
	v_exp_f32_e32 v242, v58
	v_exp_f32_e32 v243, v59
	v_exp_f32_e32 v244, v60
	v_exp_f32_e32 v245, v61
	v_fma_f32 v124, v34, s52, v94
	v_fma_f32 v125, v35, s52, v94
	v_fma_f32 v126, v36, s52, v94
	v_fma_f32 v127, v37, s52, v94
	s_waitcnt lgkmcnt(0)
	v_mfma_f32_32x32x16_bf16 v[16:31], v[226:229], v[246:249], v[16:31]
	v_exp_f32_e32 v246, v62
	v_exp_f32_e32 v247, v63
	v_fma_f32 v228, v44, s52, v94
	v_fma_f32 v229, v45, s52, v94
	v_cndmask_b32_e64 v227, v93, 1.0, s[44:45]
	v_cmp_gt_f32_e32 vcc, 1.0, v227
	s_cbranch_vccz .Lattn_rsB
	s_nop 7
	s_nop 5
	s_and_saveexec_b64 s[46:47], s[4:5]
	ds_write_b32 v216, v227 offset:128
	s_or_b64 exec, exec, s[46:47]
	s_waitcnt lgkmcnt(0)
	v_add_u32_e32 v96, v139, v187
	ds_read_b128 v[116:119], v96 offset:192
	ds_read_b128 v[92:95], v96 offset:160
	ds_read_b128 v[248:251], v96 offset:128
	ds_read_b128 v[96:99], v96 offset:224
	s_waitcnt lgkmcnt(0)
	v_mul_f32_e32 v12, v12, v96
	v_mul_f32_e32 v13, v13, v97
	v_mul_f32_e32 v14, v14, v98
	v_mul_f32_e32 v15, v15, v99
	v_mul_f32_e32 v8, v8, v116
	v_mul_f32_e32 v9, v9, v117
	v_mul_f32_e32 v10, v10, v118
	v_mul_f32_e32 v11, v11, v119
	v_mul_f32_e32 v4, v4, v92
	v_mul_f32_e32 v5, v5, v93
	v_mul_f32_e32 v6, v6, v94
	v_mul_f32_e32 v7, v7, v95
	v_mul_f32_e32 v0, v0, v248
	v_mul_f32_e32 v1, v1, v249
	v_mul_f32_e32 v2, v2, v250
	v_mul_f32_e32 v3, v3, v251
	v_mul_f32_e32 v28, v28, v96
	v_mul_f32_e32 v29, v29, v97
	v_mul_f32_e32 v30, v30, v98
	v_mul_f32_e32 v31, v31, v99
	v_mul_f32_e32 v24, v24, v116
	v_mul_f32_e32 v25, v25, v117
	v_mul_f32_e32 v26, v26, v118
	v_mul_f32_e32 v27, v27, v119
	v_mul_f32_e32 v20, v20, v92
	v_mul_f32_e32 v21, v21, v93
	v_mul_f32_e32 v22, v22, v94
	v_mul_f32_e32 v23, v23, v95
	v_mul_f32_e32 v16, v16, v248
	v_mul_f32_e32 v17, v17, v249
	v_mul_f32_e32 v18, v18, v250
	v_mul_f32_e32 v19, v19, v251
.Lattn_rsB:
	s_waitcnt lgkmcnt(0)
	s_cmp_eq_u32 s47, 0
	s_cbranch_scc0 .Lattn_gb4
	s_waitcnt lgkmcnt(0)
	s_barrier

; #define SBAR() __builtin_amdgcn_sched_barrier(0)
; #define SLOAD(i, k0) do { sr_[i].a0 = *reinterpret_cast<const bf16x8*>(&KVh[(size_t)((k0) + sr) * NKV + c16 * 8]); sr_[i].a1 = *reinterpret_cast<const bf16x8*>(&KVh[(size_t)((k0) + 32 + sr) * NKV + c16 * 8]); \
;     sr_[i].rr = *reinterpret_cast<const bf16x8*>(&KR[(size_t)((k0) + rkey) * 32 + rch * 8]); } while (0)
; template <int D0> __device__ __forceinline__ void pv_one(f32x16& od, int vb, bf16x8 pa0, bf16x8 pa1, bf16x8 pa2, bf16x8 pa3) {
;     const s16x4 l0 = tr_read<v_rd_off(D0, 0, 0)>(vb), h0 = tr_read<v_rd_off(D0, 0, 1)>(vb), l1 = tr_read<v_rd_off(D0, 1, 0)>(vb), h1 = tr_read<v_rd_off(D0, 1, 1)>(vb);
;     const s16x4 l2 = tr_read<v_rd_off(D0, 2, 0)>(vb), h2 = tr_read<v_rd_off(D0, 2, 1)>(vb), l3 = tr_read<v_rd_off(D0, 3, 0)>(vb), h3 = tr_read<v_rd_off(D0, 3, 1)>(vb);
;     asm volatile("s_waitcnt lgkmcnt(0)" ::: "memory"); SBAR();
;     ...
;     od = __builtin_amdgcn_mfma_f32_32x32x16_bf16(pa0, PK(l0, h0), od, 0, 0, 0);
;     od = __builtin_amdgcn_mfma_f32_32x32x16_bf16(pa1, PK(l1, h1), od, 0, 0, 0);
;     od = __builtin_amdgcn_mfma_f32_32x32x16_bf16(pa2, PK(l2, h2), od, 0, 0, 0);
;     od = __builtin_amdgcn_mfma_f32_32x32x16_bf16(pa3, PK(l3, h3), od, 0, 0, 0);
;     ...
; }
; __device__ __forceinline__ void attn_body(const bf16_t* __restrict__ Qb, const bf16_t* __restrict__ KVh, const bf16_t* __restrict__ KR, const float* __restrict__ ropeq,
;                                           bf16_t* __restrict__ Ob, int seq, char* lds, const int tid) {
;     ...
;         SBAR(); qkt(pA0, pA1, K_lds + bc * SHM_K, qr, r32, hi);
;         finishSM(pB0, pB1, alB, l_reg, pa0, pa1, pa2, pa3); SBAR();
;         if (j + 3 < NT) SLOAD(SE, (j + 3) * KVBLK); SBAR();
;         pv_d0(o, vb0 + bp * (int)SHM_V, pa0, pa1, pa2, pa3); partialSM(pA0, pA1, m_reg, mnA, alA);
.Lattn_slA:
	s_waitcnt lgkmcnt(5)
	v_mfma_f32_32x32x16_bf16 v[48:63], v[248:251], v[66:69], v[48:63]
	v_add_f32_e32 v244, v230, v244
	v_add_f32_e32 v245, v231, v245
	v_add_f32_e32 v176, v244, v176
	v_add_f32_e32 v177, v245, v177
	v_cvt_pk_bf16_f32 v122, v122, v123
	v_cvt_pk_bf16_f32 v123, v124, v125
	v_cvt_pk_bf16_f32 v124, v126, v127
	s_waitcnt lgkmcnt(4)
	v_mfma_f32_32x32x16_bf16 v[32:47], v[240:243], v[66:69], v[32:47]
	v_add_u32_e32 v254, s15, v215
	ds_read_b128 v[248:251], v254 offset:49152
	ds_read_b128 v[240:243], v254 offset:57344
	v_cvt_pk_bf16_f32 v125, v128, v129
	v_cvt_pk_bf16_f32 v126, v178, v179
	v_cvt_pk_bf16_f32 v127, v202, v203
	v_cvt_pk_bf16_f32 v128, v228, v229
	v_cvt_pk_bf16_f32 v129, v230, v231
	s_waitcnt lgkmcnt(3)
	v_mfma_f32_32x32x16_bf16 v[48:63], v[114:117], v[82:85], v[48:63]
	v_add_f32_e32 v178, v176, v177
	v_add_f32_e32 v179, v177, v176
	v_mov_b32_e32 v228, v178
	s_nop 1
	v_permlane32_swap_b32_e32 v178, v228
	v_permlane32_swap_b32_e32 v122, v124
	s_waitcnt lgkmcnt(2)
	v_mfma_f32_32x32x16_bf16 v[32:47], v[118:121], v[82:85], v[32:47]
	v_add_u32_e32 v246, s63, v185
	ds_read_b64_tr_b16 v[114:115], v246 offset:0
	ds_read_b64_tr_b16 v[116:117], v246 offset:2048
	ds_read_b64_tr_b16 v[118:119], v246 offset:4096
	ds_read_b64_tr_b16 v[120:121], v246 offset:6144
	v_permlane32_swap_b32_e32 v123, v125
	v_permlane32_swap_b32_e32 v126, v128
	v_permlane32_swap_b32_e32 v127, v129
	s_cmp_eq_u32 s47, 3
	s_cbranch_scc0 .Lattn_gb5
	s_waitcnt lgkmcnt(0)
	s_barrier
.Lattn_gb5:
	s_waitcnt lgkmcnt(5)
	v_mfma_f32_32x32x16_bf16 v[48:63], v[248:251], v[86:89], v[48:63]
	s_waitcnt lgkmcnt(4)
	v_mfma_f32_32x32x16_bf16 v[32:47], v[240:243], v[86:89], v[32:47]
	ds_read_b64_tr_b16 v[248:249], v246 offset:8192
	ds_read_b64_tr_b16 v[250:251], v246 offset:10240
	ds_read_b64_tr_b16 v[240:241], v246 offset:12288
	ds_read_b64_tr_b16 v[242:243], v246 offset:14336
	s_cmp_eq_u32 s47, 2
	s_cbranch_scc0 .Lattn_gb6
	s_waitcnt lgkmcnt(0)
	s_barrier
.Lattn_gb6:
	s_waitcnt lgkmcnt(6)
	v_mfma_f32_32x32x16_bf16 v[0:15], v[232:235], v[114:117], v[0:15]
	ds_read_b64_tr_b16 v[114:115], v246 offset:512
	ds_read_b64_tr_b16 v[116:117], v246 offset:2560
	v_max_f32_e32 v244, v48, v49
	v_max_f32_e32 v245, v32, v33
	v_max3_f32 v244, v244, v50, v51
	v_max3_f32 v245, v245, v34, v35
	v_max3_f32 v244, v244, v52, v53
	v_max3_f32 v245, v245, v36, v37
	v_add_f32_e32 v247, v174, v175
	v_fmac_f32_e32 v247, v225, v163
	v_add_f32_e32 v163, v178, v228
	v_fmac_f32_e32 v163, v247, v227
	s_waitcnt lgkmcnt(6)
	v_mfma_f32_32x32x16_bf16 v[0:15], v[236:239], v[118:121], v[0:15]
	ds_read_b64_tr_b16 v[118:119], v246 offset:4608
	ds_read_b64_tr_b16 v[120:121], v246 offset:6656
	v_max3_f32 v244, v244, v54, v55
	v_max3_f32 v245, v245, v38, v39
	v_max3_f32 v244, v244, v56, v57
	v_max3_f32 v245, v245, v40, v41
	v_max3_f32 v244, v244, v58, v59
	v_max3_f32 v245, v245, v42, v43
	v_max3_f32 v244, v244, v60, v61
	s_waitcnt lgkmcnt(6)
	v_mfma_f32_32x32x16_bf16 v[0:15], v[122:125], v[248:251], v[0:15]
	ds_read_b64_tr_b16 v[248:249], v246 offset:8704
	ds_read_b64_tr_b16 v[250:251], v246 offset:10752
	v_max3_f32 v245, v245, v44, v45
	v_max3_f32 v244, v244, v62, v63
	v_max3_f32 v245, v245, v46, v47
	v_max_f32_e32 v244, v244, v245
	v_mov_b32_e32 v245, v244
	s_nop 1
	v_permlane32_swap_b32_e32 v244, v245
	v_max_f32_e32 v244, v244, v245
	v_sub_f32_e32 v247, v244, v180
	s_waitcnt lgkmcnt(6)
	v_mfma_f32_32x32x16_bf16 v[0:15], v[126:129], v[240:243], v[0:15]
	ds_read_b64_tr_b16 v[240:241], v246 offset:12800
	ds_read_b64_tr_b16 v[242:243], v246 offset:14848
	v_cmp_ge_f32_e32 vcc, s67, v247
	v_max_f32_e32 v244, v180, v244
	v_sub_f32_e32 v247, v180, v244
	v_mul_f32_e32 v247, 0x3e16c740, v247
	v_exp_f32_e32 v226, v247
	s_cmp_eq_u64 vcc, exec
	s_cselect_b64 s[44:45], -1, 0
	v_cndmask_b32_e64 v179, v244, v180, s[44:45]
	s_cmp_eq_u32 s47, 1
	s_cbranch_scc0 .Lattn_gb7
	s_waitcnt lgkmcnt(0)
	s_barrier
; #define SWRITE(b, i) do { if (isK) { *(bf16x8*)(K_lds + (b) * SHM_K + kst0) = sr_[i].a0; *(bf16x8*)(K_lds + (b) * SHM_K + kst1) = sr_[i].a1; } \
;     else { *(bf16x8*)(V_lds + (b) * SHM_V + vst0) = sr_[i].a0; *(bf16x8*)(V_lds + (b) * SHM_V + vst1) = sr_[i].a1; } \
;     if (rwr) *(bf16x8*)(K_lds + (b) * SHM_K + rst) = sr_[i].rr; } while (0)
; #define SWAIT() asm volatile("s_waitcnt vmcnt(3)" ::: "memory")
; __device__ __forceinline__ void partialSM(f32x16& p0, f32x16& p1, float& m_reg, float& mn, float& alpha) {
;     constexpr float Cc = SCALE * 1.4426950408889634f;
;     float pmax = p0[0];
; #pragma unroll
;     for (int r = 1; r < 16; ++r) pmax = fmaxf(pmax, p0[r]);
; #pragma unroll
;     for (int r = 0; r < 16; ++r) pmax = fmaxf(pmax, p1[r]);
;     { auto rr = __builtin_amdgcn_permlane32_swap(__float_as_uint(pmax), __float_as_uint(pmax), false, false);
;       pmax = fmaxf(__uint_as_float(rr[0]), __uint_as_float(rr[1])); }
;     if (__builtin_expect(__all(pmax - m_reg <= THR / SCALE), 1)) { mn = m_reg; alpha = 1.f; }
;     else { mn = fmaxf(m_reg, pmax); alpha = __builtin_amdgcn_exp2f((m_reg - mn) * Cc); m_reg = mn; }
;     const float mnC = -mn * Cc;
;     { typedef float f32x2 __attribute__((ext_vector_type(2))); const f32x2 c2 = {Cc, Cc}, m2 = {mnC, mnC};
; #pragma unroll
;       for (int r = 0; r < 16; r += 2) { f32x2 t = {p0[r], p0[r + 1]}; t = __builtin_elementwise_fma(t, c2, m2); p0[r] = t.x; p0[r + 1] = t.y; }
; #pragma unroll
;       for (int r = 0; r < 16; r += 2) { f32x2 t = {p1[r], p1[r + 1]}; t = __builtin_elementwise_fma(t, c2, m2); p1[r] = t.x; p1[r + 1] = t.y; } }
; #pragma unroll
;     for (int r = 0; r < 16; ++r) p0[r] = __builtin_amdgcn_exp2f(p0[r]);
; }
; __device__ __forceinline__ void attn_body(const bf16_t* __restrict__ Qb, const bf16_t* __restrict__ KVh, const bf16_t* __restrict__ KR, const float* __restrict__ ropeq,
;                                           bf16_t* __restrict__ Ob, int seq, char* lds, const int tid) {
;     ...
;         pv_d0(o, vb0 + bp * (int)SHM_V, pa0, pa1, pa2, pa3); partialSM(pA0, pA1, m_reg, mnA, alA);
;         SWAIT(); SWRITE(bn, SO);
;         RESC(alA); __syncthreads();
;         { const int t = bp; bp = bc; bc = bn; bn = t; }
;     }
.Lattn_gb7:
	s_waitcnt lgkmcnt(6)
	v_mfma_f32_32x32x16_bf16 v[16:31], v[232:235], v[114:117], v[16:31]
	v_mul_f32_e32 v254, 0xbe16c740, v179
	v_cndmask_b32_e64 v226, v226, 1.0, s[44:45]
	v_fma_f32 v48, v48, s52, v254
	v_fma_f32 v49, v49, s52, v254
	v_fma_f32 v50, v50, s52, v254
	v_fma_f32 v51, v51, s52, v254
	v_fma_f32 v52, v52, s52, v254
	v_fma_f32 v53, v53, s52, v254
	v_fma_f32 v54, v54, s52, v254
	v_fma_f32 v55, v55, s52, v254
	v_fma_f32 v56, v56, s52, v254
	v_fma_f32 v57, v57, s52, v254
	v_fma_f32 v58, v58, s52, v254
	v_fma_f32 v59, v59, s52, v254
	v_exp_f32_e32 v116, v48
	v_exp_f32_e32 v117, v49
	v_exp_f32_e32 v114, v50
	v_exp_f32_e32 v115, v51
	s_waitcnt lgkmcnt(4)
	v_mfma_f32_32x32x16_bf16 v[16:31], v[236:239], v[118:121], v[16:31]
	v_fma_f32 v60, v60, s52, v254
	v_fma_f32 v61, v61, s52, v254
	v_fma_f32 v62, v62, s52, v254
	v_fma_f32 v63, v63, s52, v254
	v_fma_f32 v180, v32, s52, v254
	v_fma_f32 v181, v33, s52, v254
	v_fma_f32 v176, v34, s52, v254
	v_fma_f32 v177, v35, s52, v254
	v_exp_f32_e32 v112, v52
	v_exp_f32_e32 v113, v53
	v_exp_f32_e32 v110, v54
	v_exp_f32_e32 v111, v55
	v_fma_f32 v120, v44, s52, v254
	v_fma_f32 v121, v45, s52, v254
	v_fma_f32 v118, v46, s52, v254
	v_fma_f32 v119, v47, s52, v254
	s_waitcnt lgkmcnt(2)
	v_mfma_f32_32x32x16_bf16 v[16:31], v[122:125], v[248:251], v[16:31]
	v_exp_f32_e32 v108, v56
	v_exp_f32_e32 v109, v57
	v_exp_f32_e32 v106, v58
	v_exp_f32_e32 v107, v59
	v_exp_f32_e32 v102, v60
	v_exp_f32_e32 v103, v61
	v_exp_f32_e32 v104, v62
	v_exp_f32_e32 v105, v63
	v_fma_f32 v124, v40, s52, v254
	v_fma_f32 v125, v41, s52, v254
	v_fma_f32 v122, v42, s52, v254
	v_fma_f32 v123, v43, s52, v254
	s_waitcnt lgkmcnt(0)
	v_mfma_f32_32x32x16_bf16 v[16:31], v[126:129], v[240:243], v[16:31]
	v_fma_f32 v128, v36, s52, v254
	v_fma_f32 v129, v37, s52, v254
	v_fma_f32 v126, v38, s52, v254
	v_fma_f32 v127, v39, s52, v254
	v_cmp_gt_f32_e32 vcc, 1.0, v226
	s_cbranch_vccz .Lattn_rsA
	s_nop 7
	s_nop 5
	s_and_saveexec_b64 s[46:47], s[4:5]
	ds_write_b32 v216, v226 offset:128
	s_or_b64 exec, exec, s[46:47]
	s_waitcnt lgkmcnt(0)
	v_add_u32_e32 v232, v139, v187
	ds_read_b128 v[236:239], v232 offset:192
	ds_read_b128 v[240:243], v232 offset:160
	ds_read_b128 v[248:251], v232 offset:128
	ds_read_b128 v[232:235], v232 offset:224
	s_waitcnt lgkmcnt(0)
	v_mul_f32_e32 v12, v12, v232
	v_mul_f32_e32 v13, v13, v233
	v_mul_f32_e32 v14, v14, v234
	v_mul_f32_e32 v15, v15, v235
	v_mul_f32_e32 v8, v8, v236
	v_mul_f32_e32 v9, v9, v237
	v_mul_f32_e32 v10, v10, v238
	v_mul_f32_e32 v11, v11, v239
	v_mul_f32_e32 v4, v4, v240
	v_mul_f32_e32 v5, v5, v241
	v_mul_f32_e32 v6, v6, v242
	v_mul_f32_e32 v7, v7, v243
	v_mul_f32_e32 v0, v0, v248
	v_mul_f32_e32 v1, v1, v249
	v_mul_f32_e32 v2, v2, v250
	v_mul_f32_e32 v3, v3, v251
	v_mul_f32_e32 v28, v28, v232
	v_mul_f32_e32 v29, v29, v233
	v_mul_f32_e32 v30, v30, v234
	v_mul_f32_e32 v31, v31, v235
	v_mul_f32_e32 v24, v24, v236
	v_mul_f32_e32 v25, v25, v237
	v_mul_f32_e32 v26, v26, v238
	v_mul_f32_e32 v27, v27, v239
	v_mul_f32_e32 v20, v20, v240
	v_mul_f32_e32 v21, v21, v241
	v_mul_f32_e32 v22, v22, v242
	v_mul_f32_e32 v23, v23, v243
	v_mul_f32_e32 v16, v16, v248
	v_mul_f32_e32 v17, v17, v249
	v_mul_f32_e32 v18, v18, v250
	v_mul_f32_e32 v19, v19, v251
.Lattn_rsA:
	s_waitcnt lgkmcnt(0)
	s_cmp_gt_u32 s17, 60
	s_cselect_b64 s[12:13], -1, 0
	s_add_i32 s17, s17, 2
	v_lshl_add_u64 v[168:169], v[168:169], 0, s[56:57]
	v_lshl_add_u64 v[170:171], v[170:171], 0, s[24:25]
	v_lshl_add_u64 v[172:173], v[172:173], 0, s[24:25]
	s_cmp_eq_u32 s47, 0
	s_cbranch_scc0 .Lattn_gb8
	s_waitcnt lgkmcnt(0)
	s_barrier
